# hand-written epilogues of the two split-K remainder GEMMs too (permlane16_swap pairing, dwordx4 PART stores)
# speedup vs baseline: 1.0106x; 1.0106x over previous
; __device__ __forceinline__ unsigned cvt_pk_bf16(float lo, float hi) { unsigned r; asm("v_cvt_pk_bf16_f32 %0, %1, %2" : "=v"(r) : "v"(lo), "v"(hi)); return r; }
;     __device__ __forceinline__ void operator()(const f32x4 (&acc)[2][2][4][2], const pg8::Unit& u, int wr, int wc, int fr, int fq) const {
;         bf16_t* base = P + ((size_t)(u.tl * 8 + u.ks) << 16) + (size_t)(wr * 64 + fr) * 256 + wc * 32 + 4 * fq;
;         const int row0 = u.pm * 256 + wr * 64 + fr, col0 = u.pn * 256 + wc * 32 + 4 * fq;
;         f32x4 swv[2][2];
; #pragma unroll
;         for (int bj = 0; bj < 2; ++bj)
; #pragma unroll
;             for (int n = 0; n < 2; ++n) swv[bj][n] = *(const f32x4*)(sw + col0 + bj * 128 + n * 16);
; #pragma unroll
;         for (int ai = 0; ai < 2; ++ai)
; #pragma unroll
;             for (int m = 0; m < 4; ++m) { const float sav = sa[row0 + ai * 128 + m * 16];
; #pragma unroll
;                 for (int bj = 0; bj < 2; ++bj)
; #pragma unroll
;                     for (int n = 0; n < 2; ++n) { const i32x4 q = __builtin_bit_cast(i32x4, acc[ai][bj][m][n]);
;                         const f32x4 v = (f32x4){(float)q[0], (float)q[1], (float)q[2], (float)q[3]} * swv[bj][n] * sav;
;                         u32x2 o; o.x = cvt_pk_bf16(v[0], v[1]); o.y = cvt_pk_bf16(v[2], v[3]);
;                         *(u32x2*)(base + (size_t)(ai * 128 + m * 16) * 256 + bj * 128 + n * 16) = o; } }
;     }
.LBB0_2246:
	v_lshl_add_u32 v160, s31, 8, v150
	v_and_b32_e32 v161, 1, v235
	v_mul_u32_u24_e32 v161, 12, v161
	v_lshl_add_u32 v161, v235, 2, v161
	v_add_u32_e32 v161, s3, v161
	v_lshlrev_b32_e32 v164, 9, v150
	v_lshl_add_u32 v164, v161, 1, v164
	v_lshl_or_b32 v161, s35, 8, v161
	v_lshlrev_b32_e32 v162, 2, v160
	v_lshlrev_b32_e32 v163, 2, v161
	global_load_dword v168, v162, s[6:7] offset:0
	global_load_dword v169, v162, s[6:7] offset:64
	global_load_dword v170, v162, s[6:7] offset:128
	global_load_dword v171, v162, s[6:7] offset:192
	global_load_dword v172, v162, s[6:7] offset:512
	global_load_dword v173, v162, s[6:7] offset:576
	global_load_dword v174, v162, s[6:7] offset:640
	global_load_dword v175, v162, s[6:7] offset:704
	global_load_dwordx4 v[176:179], v163, s[8:9] offset:0
	global_load_dwordx4 v[180:183], v163, s[8:9] offset:16
	global_load_dwordx4 v[184:187], v163, s[8:9] offset:512
	global_load_dwordx4 v[188:191], v163, s[8:9] offset:528
	s_lshl_b32 s4, s30, 3
	s_add_i32 s4, s4, s2
	s_ashr_i32 s5, s4, 31
	s_lshl_b64 s[4:5], s[4:5], 17
	s_add_u32 s4, s86, s4
	s_addc_u32 s5, s87, s5
	s_add_u32 s4, s4, 0x2a50f000
	s_addc_u32 s5, s5, 0
	v_permlane16_swap_b32_e32 v142, v122
	v_permlane16_swap_b32_e32 v143, v123
	v_permlane16_swap_b32_e32 v144, v124
	v_permlane16_swap_b32_e32 v145, v125
	v_cvt_f32_i32_e32 v142, v142
	v_cvt_f32_i32_e32 v143, v143
	v_cvt_f32_i32_e32 v144, v144
	v_cvt_f32_i32_e32 v145, v145
	v_cvt_f32_i32_e32 v122, v122
	v_cvt_f32_i32_e32 v123, v123
	v_cvt_f32_i32_e32 v124, v124
	v_cvt_f32_i32_e32 v125, v125
	s_waitcnt vmcnt(0)
	v_pk_mul_f32 v[142:143], v[142:143], v[176:177]
	v_pk_mul_f32 v[144:145], v[144:145], v[178:179]
	v_pk_mul_f32 v[122:123], v[122:123], v[180:181]
	v_pk_mul_f32 v[124:125], v[124:125], v[182:183]
	v_mul_f32_e32 v142, v142, v168
	v_mul_f32_e32 v143, v143, v168
	v_mul_f32_e32 v144, v144, v168
	v_mul_f32_e32 v145, v145, v168
	v_mul_f32_e32 v122, v122, v168
	v_mul_f32_e32 v123, v123, v168
	v_mul_f32_e32 v124, v124, v168
	v_mul_f32_e32 v125, v125, v168
	v_cvt_pk_bf16_f32 v142, v142, v143
	v_cvt_pk_bf16_f32 v143, v144, v145
	v_cvt_pk_bf16_f32 v144, v122, v123
	v_cvt_pk_bf16_f32 v145, v124, v125
	v_mov_b32_e32 v165, v164
	global_store_dwordx4 v165, v[142:145], s[4:5] offset:0
	v_permlane16_swap_b32_e32 v118, v114
	v_permlane16_swap_b32_e32 v119, v115
	v_permlane16_swap_b32_e32 v120, v116
	v_permlane16_swap_b32_e32 v121, v117
	v_cvt_f32_i32_e32 v118, v118
	v_cvt_f32_i32_e32 v119, v119
	v_cvt_f32_i32_e32 v120, v120
	v_cvt_f32_i32_e32 v121, v121
	v_cvt_f32_i32_e32 v114, v114
	v_cvt_f32_i32_e32 v115, v115
	v_cvt_f32_i32_e32 v116, v116
	v_cvt_f32_i32_e32 v117, v117
	v_pk_mul_f32 v[118:119], v[118:119], v[184:185]
	v_pk_mul_f32 v[120:121], v[120:121], v[186:187]
	v_pk_mul_f32 v[114:115], v[114:115], v[188:189]
	v_pk_mul_f32 v[116:117], v[116:117], v[190:191]
	v_mul_f32_e32 v118, v118, v168
	v_mul_f32_e32 v119, v119, v168
	v_mul_f32_e32 v120, v120, v168
	v_mul_f32_e32 v121, v121, v168
	v_mul_f32_e32 v114, v114, v168
	v_mul_f32_e32 v115, v115, v168
	v_mul_f32_e32 v116, v116, v168
	v_mul_f32_e32 v117, v117, v168
	v_cvt_pk_bf16_f32 v118, v118, v119
	v_cvt_pk_bf16_f32 v119, v120, v121
	v_cvt_pk_bf16_f32 v120, v114, v115
	v_cvt_pk_bf16_f32 v121, v116, v117
	v_mov_b32_e32 v166, v164
	global_store_dwordx4 v166, v[118:121], s[4:5] offset:256
	v_permlane16_swap_b32_e32 v110, v106
	v_permlane16_swap_b32_e32 v111, v107
	v_permlane16_swap_b32_e32 v112, v108
	v_permlane16_swap_b32_e32 v113, v109
	v_cvt_f32_i32_e32 v110, v110
	v_cvt_f32_i32_e32 v111, v111
	v_cvt_f32_i32_e32 v112, v112
	v_cvt_f32_i32_e32 v113, v113
	v_cvt_f32_i32_e32 v106, v106
	v_cvt_f32_i32_e32 v107, v107
	v_cvt_f32_i32_e32 v108, v108
	v_cvt_f32_i32_e32 v109, v109
	v_pk_mul_f32 v[110:111], v[110:111], v[176:177]
	v_pk_mul_f32 v[112:113], v[112:113], v[178:179]
	v_pk_mul_f32 v[106:107], v[106:107], v[180:181]
	v_pk_mul_f32 v[108:109], v[108:109], v[182:183]
	v_mul_f32_e32 v110, v110, v169
	v_mul_f32_e32 v111, v111, v169
	v_mul_f32_e32 v112, v112, v169
	v_mul_f32_e32 v113, v113, v169
	v_mul_f32_e32 v106, v106, v169
	v_mul_f32_e32 v107, v107, v169
	v_mul_f32_e32 v108, v108, v169
	v_mul_f32_e32 v109, v109, v169
	v_cvt_pk_bf16_f32 v110, v110, v111
	v_cvt_pk_bf16_f32 v111, v112, v113
	v_cvt_pk_bf16_f32 v112, v106, v107
	v_cvt_pk_bf16_f32 v113, v108, v109
	v_add_u32_e32 v165, 0x2000, v164
	global_store_dwordx4 v165, v[110:113], s[4:5] offset:0
	v_permlane16_swap_b32_e32 v102, v98
	v_permlane16_swap_b32_e32 v103, v99
	v_permlane16_swap_b32_e32 v104, v100
	v_permlane16_swap_b32_e32 v105, v101
	v_cvt_f32_i32_e32 v102, v102
	v_cvt_f32_i32_e32 v103, v103
	v_cvt_f32_i32_e32 v104, v104
	v_cvt_f32_i32_e32 v105, v105
	v_cvt_f32_i32_e32 v98, v98
	v_cvt_f32_i32_e32 v99, v99
	v_cvt_f32_i32_e32 v100, v100
	v_cvt_f32_i32_e32 v101, v101
	v_pk_mul_f32 v[102:103], v[102:103], v[184:185]
	v_pk_mul_f32 v[104:105], v[104:105], v[186:187]
	v_pk_mul_f32 v[98:99], v[98:99], v[188:189]
	v_pk_mul_f32 v[100:101], v[100:101], v[190:191]
	v_mul_f32_e32 v102, v102, v169
	v_mul_f32_e32 v103, v103, v169
	v_mul_f32_e32 v104, v104, v169
	v_mul_f32_e32 v105, v105, v169
	v_mul_f32_e32 v98, v98, v169
	v_mul_f32_e32 v99, v99, v169
	v_mul_f32_e32 v100, v100, v169
	v_mul_f32_e32 v101, v101, v169
	v_cvt_pk_bf16_f32 v102, v102, v103
	v_cvt_pk_bf16_f32 v103, v104, v105
	v_cvt_pk_bf16_f32 v104, v98, v99
	v_cvt_pk_bf16_f32 v105, v100, v101
	v_add_u32_e32 v166, 0x2000, v164
	global_store_dwordx4 v166, v[102:105], s[4:5] offset:256
	v_permlane16_swap_b32_e32 v94, v90
	v_permlane16_swap_b32_e32 v95, v91
	v_permlane16_swap_b32_e32 v96, v92
	v_permlane16_swap_b32_e32 v97, v93
	v_cvt_f32_i32_e32 v94, v94
; __device__ __forceinline__ unsigned cvt_pk_bf16(float lo, float hi) { unsigned r; asm("v_cvt_pk_bf16_f32 %0, %1, %2" : "=v"(r) : "v"(lo), "v"(hi)); return r; }
;     __device__ __forceinline__ void operator()(const f32x4 (&acc)[2][2][4][2], const pg8::Unit& u, int wr, int wc, int fr, int fq) const {
;         bf16_t* base = P + ((size_t)(u.tl * 8 + u.ks) << 16) + (size_t)(wr * 64 + fr) * 256 + wc * 32 + 4 * fq;
;         const int row0 = u.pm * 256 + wr * 64 + fr, col0 = u.pn * 256 + wc * 32 + 4 * fq;
;         f32x4 swv[2][2];
; #pragma unroll
;         for (int bj = 0; bj < 2; ++bj)
; #pragma unroll
;             for (int n = 0; n < 2; ++n) swv[bj][n] = *(const f32x4*)(sw + col0 + bj * 128 + n * 16);
; #pragma unroll
;         for (int ai = 0; ai < 2; ++ai)
; #pragma unroll
;             for (int m = 0; m < 4; ++m) { const float sav = sa[row0 + ai * 128 + m * 16];
; #pragma unroll
;                 for (int bj = 0; bj < 2; ++bj)
; #pragma unroll
;                     for (int n = 0; n < 2; ++n) { const i32x4 q = __builtin_bit_cast(i32x4, acc[ai][bj][m][n]);
;                         const f32x4 v = (f32x4){(float)q[0], (float)q[1], (float)q[2], (float)q[3]} * swv[bj][n] * sav;
;                         u32x2 o; o.x = cvt_pk_bf16(v[0], v[1]); o.y = cvt_pk_bf16(v[2], v[3]);
;                         *(u32x2*)(base + (size_t)(ai * 128 + m * 16) * 256 + bj * 128 + n * 16) = o; } }
;     }
	v_cvt_f32_i32_e32 v95, v95
	v_cvt_f32_i32_e32 v96, v96
	v_cvt_f32_i32_e32 v97, v97
	v_cvt_f32_i32_e32 v90, v90
	v_cvt_f32_i32_e32 v91, v91
	v_cvt_f32_i32_e32 v92, v92
	v_cvt_f32_i32_e32 v93, v93
	v_pk_mul_f32 v[94:95], v[94:95], v[176:177]
	v_pk_mul_f32 v[96:97], v[96:97], v[178:179]
	v_pk_mul_f32 v[90:91], v[90:91], v[180:181]
	v_pk_mul_f32 v[92:93], v[92:93], v[182:183]
	v_mul_f32_e32 v94, v94, v170
	v_mul_f32_e32 v95, v95, v170
	v_mul_f32_e32 v96, v96, v170
	v_mul_f32_e32 v97, v97, v170
	v_mul_f32_e32 v90, v90, v170
	v_mul_f32_e32 v91, v91, v170
	v_mul_f32_e32 v92, v92, v170
	v_mul_f32_e32 v93, v93, v170
	v_cvt_pk_bf16_f32 v94, v94, v95
	v_cvt_pk_bf16_f32 v95, v96, v97
	v_cvt_pk_bf16_f32 v96, v90, v91
	v_cvt_pk_bf16_f32 v97, v92, v93
	v_add_u32_e32 v165, 0x4000, v164
	global_store_dwordx4 v165, v[94:97], s[4:5] offset:0
	v_permlane16_swap_b32_e32 v86, v82
	v_permlane16_swap_b32_e32 v87, v83
	v_permlane16_swap_b32_e32 v88, v84
	v_permlane16_swap_b32_e32 v89, v85
	v_cvt_f32_i32_e32 v86, v86
	v_cvt_f32_i32_e32 v87, v87
	v_cvt_f32_i32_e32 v88, v88
	v_cvt_f32_i32_e32 v89, v89
	v_cvt_f32_i32_e32 v82, v82
	v_cvt_f32_i32_e32 v83, v83
	v_cvt_f32_i32_e32 v84, v84
	v_cvt_f32_i32_e32 v85, v85
	v_pk_mul_f32 v[86:87], v[86:87], v[184:185]
	v_pk_mul_f32 v[88:89], v[88:89], v[186:187]
	v_pk_mul_f32 v[82:83], v[82:83], v[188:189]
	v_pk_mul_f32 v[84:85], v[84:85], v[190:191]
	v_mul_f32_e32 v86, v86, v170
	v_mul_f32_e32 v87, v87, v170
	v_mul_f32_e32 v88, v88, v170
	v_mul_f32_e32 v89, v89, v170
	v_mul_f32_e32 v82, v82, v170
	v_mul_f32_e32 v83, v83, v170
	v_mul_f32_e32 v84, v84, v170
	v_mul_f32_e32 v85, v85, v170
	v_cvt_pk_bf16_f32 v86, v86, v87
	v_cvt_pk_bf16_f32 v87, v88, v89
	v_cvt_pk_bf16_f32 v88, v82, v83
	v_cvt_pk_bf16_f32 v89, v84, v85
	v_add_u32_e32 v166, 0x4000, v164
	global_store_dwordx4 v166, v[86:89], s[4:5] offset:256
	v_permlane16_swap_b32_e32 v78, v74
	v_permlane16_swap_b32_e32 v79, v75
	v_permlane16_swap_b32_e32 v80, v76
	v_permlane16_swap_b32_e32 v81, v77
	v_cvt_f32_i32_e32 v78, v78
	v_cvt_f32_i32_e32 v79, v79
	v_cvt_f32_i32_e32 v80, v80
	v_cvt_f32_i32_e32 v81, v81
	v_cvt_f32_i32_e32 v74, v74
	v_cvt_f32_i32_e32 v75, v75
	v_cvt_f32_i32_e32 v76, v76
	v_cvt_f32_i32_e32 v77, v77
	v_pk_mul_f32 v[78:79], v[78:79], v[176:177]
	v_pk_mul_f32 v[80:81], v[80:81], v[178:179]
	v_pk_mul_f32 v[74:75], v[74:75], v[180:181]
	v_pk_mul_f32 v[76:77], v[76:77], v[182:183]
	v_mul_f32_e32 v78, v78, v171
	v_mul_f32_e32 v79, v79, v171
	v_mul_f32_e32 v80, v80, v171
	v_mul_f32_e32 v81, v81, v171
	v_mul_f32_e32 v74, v74, v171
	v_mul_f32_e32 v75, v75, v171
	v_mul_f32_e32 v76, v76, v171
	v_mul_f32_e32 v77, v77, v171
	v_cvt_pk_bf16_f32 v78, v78, v79
	v_cvt_pk_bf16_f32 v79, v80, v81
	v_cvt_pk_bf16_f32 v80, v74, v75
	v_cvt_pk_bf16_f32 v81, v76, v77
	v_add_u32_e32 v165, 0x6000, v164
	global_store_dwordx4 v165, v[78:81], s[4:5] offset:0
	v_permlane16_swap_b32_e32 v70, v66
	v_permlane16_swap_b32_e32 v71, v67
	v_permlane16_swap_b32_e32 v72, v68
	v_permlane16_swap_b32_e32 v73, v69
	v_cvt_f32_i32_e32 v70, v70
	v_cvt_f32_i32_e32 v71, v71
	v_cvt_f32_i32_e32 v72, v72
	v_cvt_f32_i32_e32 v73, v73
	v_cvt_f32_i32_e32 v66, v66
	v_cvt_f32_i32_e32 v67, v67
	v_cvt_f32_i32_e32 v68, v68
	v_cvt_f32_i32_e32 v69, v69
	v_pk_mul_f32 v[70:71], v[70:71], v[184:185]
	v_pk_mul_f32 v[72:73], v[72:73], v[186:187]
	v_pk_mul_f32 v[66:67], v[66:67], v[188:189]
	v_pk_mul_f32 v[68:69], v[68:69], v[190:191]
	v_mul_f32_e32 v70, v70, v171
	v_mul_f32_e32 v71, v71, v171
	v_mul_f32_e32 v72, v72, v171
	v_mul_f32_e32 v73, v73, v171
	v_mul_f32_e32 v66, v66, v171
	v_mul_f32_e32 v67, v67, v171
	v_mul_f32_e32 v68, v68, v171
	v_mul_f32_e32 v69, v69, v171
	v_cvt_pk_bf16_f32 v70, v70, v71
	v_cvt_pk_bf16_f32 v71, v72, v73
	v_cvt_pk_bf16_f32 v72, v66, v67
	v_cvt_pk_bf16_f32 v73, v68, v69
	v_add_u32_e32 v166, 0x6000, v164
	global_store_dwordx4 v166, v[70:73], s[4:5] offset:256
	v_permlane16_swap_b32_e32 v62, v58
	v_permlane16_swap_b32_e32 v63, v59
	v_permlane16_swap_b32_e32 v64, v60
	v_permlane16_swap_b32_e32 v65, v61
	v_cvt_f32_i32_e32 v62, v62
	v_cvt_f32_i32_e32 v63, v63
	v_cvt_f32_i32_e32 v64, v64
	v_cvt_f32_i32_e32 v65, v65
	v_cvt_f32_i32_e32 v58, v58
	v_cvt_f32_i32_e32 v59, v59
	v_cvt_f32_i32_e32 v60, v60
	v_cvt_f32_i32_e32 v61, v61
	v_pk_mul_f32 v[62:63], v[62:63], v[176:177]
	v_pk_mul_f32 v[64:65], v[64:65], v[178:179]
	v_pk_mul_f32 v[58:59], v[58:59], v[180:181]
	v_pk_mul_f32 v[60:61], v[60:61], v[182:183]
	v_mul_f32_e32 v62, v62, v172
	v_mul_f32_e32 v63, v63, v172
	v_mul_f32_e32 v64, v64, v172
	v_mul_f32_e32 v65, v65, v172
	v_mul_f32_e32 v58, v58, v172
	v_mul_f32_e32 v59, v59, v172
	v_mul_f32_e32 v60, v60, v172
	v_mul_f32_e32 v61, v61, v172
	v_cvt_pk_bf16_f32 v62, v62, v63
	v_cvt_pk_bf16_f32 v63, v64, v65
	v_cvt_pk_bf16_f32 v64, v58, v59
	v_cvt_pk_bf16_f32 v65, v60, v61
	v_add_u32_e32 v165, 0x10000, v164
	global_store_dwordx4 v165, v[62:65], s[4:5] offset:0
	v_permlane16_swap_b32_e32 v54, v50
	v_permlane16_swap_b32_e32 v55, v51
	v_permlane16_swap_b32_e32 v56, v52
	v_permlane16_swap_b32_e32 v57, v53
	v_cvt_f32_i32_e32 v54, v54
	v_cvt_f32_i32_e32 v55, v55
	v_cvt_f32_i32_e32 v56, v56
	v_cvt_f32_i32_e32 v57, v57
	v_cvt_f32_i32_e32 v50, v50
	v_cvt_f32_i32_e32 v51, v51
	v_cvt_f32_i32_e32 v52, v52
	v_cvt_f32_i32_e32 v53, v53
	v_pk_mul_f32 v[54:55], v[54:55], v[184:185]
	v_pk_mul_f32 v[56:57], v[56:57], v[186:187]
	v_pk_mul_f32 v[50:51], v[50:51], v[188:189]
	v_pk_mul_f32 v[52:53], v[52:53], v[190:191]
	v_mul_f32_e32 v54, v54, v172
	v_mul_f32_e32 v55, v55, v172
	v_mul_f32_e32 v56, v56, v172
	v_mul_f32_e32 v57, v57, v172
	v_mul_f32_e32 v50, v50, v172
	v_mul_f32_e32 v51, v51, v172
	v_mul_f32_e32 v52, v52, v172
; __device__ __forceinline__ unsigned cvt_pk_bf16(float lo, float hi) { unsigned r; asm("v_cvt_pk_bf16_f32 %0, %1, %2" : "=v"(r) : "v"(lo), "v"(hi)); return r; }
; #define PG8_WAIT_V(n) asm volatile("s_waitcnt vmcnt(" #n ")" ::: "memory")
; #define PG8_BAR __builtin_amdgcn_s_barrier()
; template <class Epi, class Geom, class Sched, bool ALIGN_EPI, bool I8 = false>
; __device__ __forceinline__ void gemm_phase(LAS unsigned char* lds, const Gemm g, const Sched& S, const Epi& E) {
;     ...
;     PG8_WAIT_V(0);
;     if constexpr (!ALIGN_EPI) { if (wr == 0) PG8_BAR; }
;     PG8_BAR;
;     __device__ __forceinline__ void operator()(const f32x4 (&acc)[2][2][4][2], const pg8::Unit& u, int wr, int wc, int fr, int fq) const {
;         bf16_t* base = P + ((size_t)(u.tl * 8 + u.ks) << 16) + (size_t)(wr * 64 + fr) * 256 + wc * 32 + 4 * fq;
;         const int row0 = u.pm * 256 + wr * 64 + fr, col0 = u.pn * 256 + wc * 32 + 4 * fq;
;         f32x4 swv[2][2];
; #pragma unroll
;         for (int bj = 0; bj < 2; ++bj)
; #pragma unroll
;             for (int n = 0; n < 2; ++n) swv[bj][n] = *(const f32x4*)(sw + col0 + bj * 128 + n * 16);
; #pragma unroll
;         for (int ai = 0; ai < 2; ++ai)
; #pragma unroll
;             for (int m = 0; m < 4; ++m) { const float sav = sa[row0 + ai * 128 + m * 16];
; #pragma unroll
;                 for (int bj = 0; bj < 2; ++bj)
; #pragma unroll
;                     for (int n = 0; n < 2; ++n) { const i32x4 q = __builtin_bit_cast(i32x4, acc[ai][bj][m][n]);
;                         const f32x4 v = (f32x4){(float)q[0], (float)q[1], (float)q[2], (float)q[3]} * swv[bj][n] * sav;
;                         u32x2 o; o.x = cvt_pk_bf16(v[0], v[1]); o.y = cvt_pk_bf16(v[2], v[3]);
;                         *(u32x2*)(base + (size_t)(ai * 128 + m * 16) * 256 + bj * 128 + n * 16) = o; } }
;     }
	v_mul_f32_e32 v53, v53, v172
	v_cvt_pk_bf16_f32 v54, v54, v55
	v_cvt_pk_bf16_f32 v55, v56, v57
	v_cvt_pk_bf16_f32 v56, v50, v51
	v_cvt_pk_bf16_f32 v57, v52, v53
	v_add_u32_e32 v166, 0x10000, v164
	global_store_dwordx4 v166, v[54:57], s[4:5] offset:256
	v_permlane16_swap_b32_e32 v46, v42
	v_permlane16_swap_b32_e32 v47, v43
	v_permlane16_swap_b32_e32 v48, v44
	v_permlane16_swap_b32_e32 v49, v45
	v_cvt_f32_i32_e32 v46, v46
	v_cvt_f32_i32_e32 v47, v47
	v_cvt_f32_i32_e32 v48, v48
	v_cvt_f32_i32_e32 v49, v49
	v_cvt_f32_i32_e32 v42, v42
	v_cvt_f32_i32_e32 v43, v43
	v_cvt_f32_i32_e32 v44, v44
	v_cvt_f32_i32_e32 v45, v45
	v_pk_mul_f32 v[46:47], v[46:47], v[176:177]
	v_pk_mul_f32 v[48:49], v[48:49], v[178:179]
	v_pk_mul_f32 v[42:43], v[42:43], v[180:181]
	v_pk_mul_f32 v[44:45], v[44:45], v[182:183]
	v_mul_f32_e32 v46, v46, v173
	v_mul_f32_e32 v47, v47, v173
	v_mul_f32_e32 v48, v48, v173
	v_mul_f32_e32 v49, v49, v173
	v_mul_f32_e32 v42, v42, v173
	v_mul_f32_e32 v43, v43, v173
	v_mul_f32_e32 v44, v44, v173
	v_mul_f32_e32 v45, v45, v173
	v_cvt_pk_bf16_f32 v46, v46, v47
	v_cvt_pk_bf16_f32 v47, v48, v49
	v_cvt_pk_bf16_f32 v48, v42, v43
	v_cvt_pk_bf16_f32 v49, v44, v45
	v_add_u32_e32 v165, 0x12000, v164
	global_store_dwordx4 v165, v[46:49], s[4:5] offset:0
	v_permlane16_swap_b32_e32 v38, v34
	v_permlane16_swap_b32_e32 v39, v35
	v_permlane16_swap_b32_e32 v40, v36
	v_permlane16_swap_b32_e32 v41, v37
	v_cvt_f32_i32_e32 v38, v38
	v_cvt_f32_i32_e32 v39, v39
	v_cvt_f32_i32_e32 v40, v40
	v_cvt_f32_i32_e32 v41, v41
	v_cvt_f32_i32_e32 v34, v34
	v_cvt_f32_i32_e32 v35, v35
	v_cvt_f32_i32_e32 v36, v36
	v_cvt_f32_i32_e32 v37, v37
	v_pk_mul_f32 v[38:39], v[38:39], v[184:185]
	v_pk_mul_f32 v[40:41], v[40:41], v[186:187]
	v_pk_mul_f32 v[34:35], v[34:35], v[188:189]
	v_pk_mul_f32 v[36:37], v[36:37], v[190:191]
	v_mul_f32_e32 v38, v38, v173
	v_mul_f32_e32 v39, v39, v173
	v_mul_f32_e32 v40, v40, v173
	v_mul_f32_e32 v41, v41, v173
	v_mul_f32_e32 v34, v34, v173
	v_mul_f32_e32 v35, v35, v173
	v_mul_f32_e32 v36, v36, v173
	v_mul_f32_e32 v37, v37, v173
	v_cvt_pk_bf16_f32 v38, v38, v39
	v_cvt_pk_bf16_f32 v39, v40, v41
	v_cvt_pk_bf16_f32 v40, v34, v35
	v_cvt_pk_bf16_f32 v41, v36, v37
	v_add_u32_e32 v166, 0x12000, v164
	global_store_dwordx4 v166, v[38:41], s[4:5] offset:256
	v_permlane16_swap_b32_e32 v30, v26
	v_permlane16_swap_b32_e32 v31, v27
	v_permlane16_swap_b32_e32 v32, v28
	v_permlane16_swap_b32_e32 v33, v29
	v_cvt_f32_i32_e32 v30, v30
	v_cvt_f32_i32_e32 v31, v31
	v_cvt_f32_i32_e32 v32, v32
	v_cvt_f32_i32_e32 v33, v33
	v_cvt_f32_i32_e32 v26, v26
	v_cvt_f32_i32_e32 v27, v27
	v_cvt_f32_i32_e32 v28, v28
	v_cvt_f32_i32_e32 v29, v29
	v_pk_mul_f32 v[30:31], v[30:31], v[176:177]
	v_pk_mul_f32 v[32:33], v[32:33], v[178:179]
	v_pk_mul_f32 v[26:27], v[26:27], v[180:181]
	v_pk_mul_f32 v[28:29], v[28:29], v[182:183]
	v_mul_f32_e32 v30, v30, v174
	v_mul_f32_e32 v31, v31, v174
	v_mul_f32_e32 v32, v32, v174
	v_mul_f32_e32 v33, v33, v174
	v_mul_f32_e32 v26, v26, v174
	v_mul_f32_e32 v27, v27, v174
	v_mul_f32_e32 v28, v28, v174
	v_mul_f32_e32 v29, v29, v174
	v_cvt_pk_bf16_f32 v30, v30, v31
	v_cvt_pk_bf16_f32 v31, v32, v33
	v_cvt_pk_bf16_f32 v32, v26, v27
	v_cvt_pk_bf16_f32 v33, v28, v29
	v_add_u32_e32 v165, 0x14000, v164
	global_store_dwordx4 v165, v[30:33], s[4:5] offset:0
	v_permlane16_swap_b32_e32 v22, v18
	v_permlane16_swap_b32_e32 v23, v19
	v_permlane16_swap_b32_e32 v24, v20
	v_permlane16_swap_b32_e32 v25, v21
	v_cvt_f32_i32_e32 v22, v22
	v_cvt_f32_i32_e32 v23, v23
	v_cvt_f32_i32_e32 v24, v24
	v_cvt_f32_i32_e32 v25, v25
	v_cvt_f32_i32_e32 v18, v18
	v_cvt_f32_i32_e32 v19, v19
	v_cvt_f32_i32_e32 v20, v20
	v_cvt_f32_i32_e32 v21, v21
	v_pk_mul_f32 v[22:23], v[22:23], v[184:185]
	v_pk_mul_f32 v[24:25], v[24:25], v[186:187]
	v_pk_mul_f32 v[18:19], v[18:19], v[188:189]
	v_pk_mul_f32 v[20:21], v[20:21], v[190:191]
	v_mul_f32_e32 v22, v22, v174
	v_mul_f32_e32 v23, v23, v174
	v_mul_f32_e32 v24, v24, v174
	v_mul_f32_e32 v25, v25, v174
	v_mul_f32_e32 v18, v18, v174
	v_mul_f32_e32 v19, v19, v174
	v_mul_f32_e32 v20, v20, v174
	v_mul_f32_e32 v21, v21, v174
	v_cvt_pk_bf16_f32 v22, v22, v23
	v_cvt_pk_bf16_f32 v23, v24, v25
	v_cvt_pk_bf16_f32 v24, v18, v19
	v_cvt_pk_bf16_f32 v25, v20, v21
	v_add_u32_e32 v166, 0x14000, v164
	global_store_dwordx4 v166, v[22:25], s[4:5] offset:256
	v_permlane16_swap_b32_e32 v14, v10
	v_permlane16_swap_b32_e32 v15, v11
	v_permlane16_swap_b32_e32 v16, v12
	v_permlane16_swap_b32_e32 v17, v13
	v_cvt_f32_i32_e32 v14, v14
	v_cvt_f32_i32_e32 v15, v15
	v_cvt_f32_i32_e32 v16, v16
	v_cvt_f32_i32_e32 v17, v17
	v_cvt_f32_i32_e32 v10, v10
	v_cvt_f32_i32_e32 v11, v11
	v_cvt_f32_i32_e32 v12, v12
	v_cvt_f32_i32_e32 v13, v13
	v_pk_mul_f32 v[14:15], v[14:15], v[176:177]
	v_pk_mul_f32 v[16:17], v[16:17], v[178:179]
	v_pk_mul_f32 v[10:11], v[10:11], v[180:181]
	v_pk_mul_f32 v[12:13], v[12:13], v[182:183]
	v_mul_f32_e32 v14, v14, v175
	v_mul_f32_e32 v15, v15, v175
	v_mul_f32_e32 v16, v16, v175
	v_mul_f32_e32 v17, v17, v175
	v_mul_f32_e32 v10, v10, v175
	v_mul_f32_e32 v11, v11, v175
	v_mul_f32_e32 v12, v12, v175
	v_mul_f32_e32 v13, v13, v175
	v_cvt_pk_bf16_f32 v14, v14, v15
	v_cvt_pk_bf16_f32 v15, v16, v17
	v_cvt_pk_bf16_f32 v16, v10, v11
	v_cvt_pk_bf16_f32 v17, v12, v13
	v_add_u32_e32 v165, 0x16000, v164
	global_store_dwordx4 v165, v[14:17], s[4:5] offset:0
	v_permlane16_swap_b32_e32 v6, v2
	v_permlane16_swap_b32_e32 v7, v3
	v_permlane16_swap_b32_e32 v8, v4
	v_permlane16_swap_b32_e32 v9, v5
	v_cvt_f32_i32_e32 v6, v6
	v_cvt_f32_i32_e32 v7, v7
	v_cvt_f32_i32_e32 v8, v8
	v_cvt_f32_i32_e32 v9, v9
	v_cvt_f32_i32_e32 v2, v2
	v_cvt_f32_i32_e32 v3, v3
	v_cvt_f32_i32_e32 v4, v4
	v_cvt_f32_i32_e32 v5, v5
	v_pk_mul_f32 v[6:7], v[6:7], v[184:185]
	v_pk_mul_f32 v[8:9], v[8:9], v[186:187]
	v_pk_mul_f32 v[2:3], v[2:3], v[188:189]
	v_pk_mul_f32 v[4:5], v[4:5], v[190:191]
	v_mul_f32_e32 v6, v6, v175
	v_mul_f32_e32 v7, v7, v175
	v_mul_f32_e32 v8, v8, v175
	v_mul_f32_e32 v9, v9, v175
	v_mul_f32_e32 v2, v2, v175
	v_mul_f32_e32 v3, v3, v175
	v_mul_f32_e32 v4, v4, v175
	v_mul_f32_e32 v5, v5, v175
	v_cvt_pk_bf16_f32 v6, v6, v7
	v_cvt_pk_bf16_f32 v7, v8, v9
	v_cvt_pk_bf16_f32 v8, v2, v3
	v_cvt_pk_bf16_f32 v9, v4, v5
	v_add_u32_e32 v166, 0x16000, v164
	global_store_dwordx4 v166, v[6:9], s[4:5] offset:256
	s_waitcnt vmcnt(0)
	s_barrier

; __device__ __forceinline__ unsigned cvt_pk_bf16(float lo, float hi) { unsigned r; asm("v_cvt_pk_bf16_f32 %0, %1, %2" : "=v"(r) : "v"(lo), "v"(hi)); return r; }
;     __device__ __forceinline__ void operator()(const f32x4 (&acc)[2][2][4][2], const pg8::Unit& u, int wr, int wc, int fr, int fq) const {
;         bf16_t* base = P + ((size_t)(u.tl * 8 + u.ks) << 16) + (size_t)(wr * 64 + fr) * 256 + wc * 32 + 4 * fq;
;         const int row0 = u.pm * 256 + wr * 64 + fr, col0 = u.pn * 256 + wc * 32 + 4 * fq;
;         f32x4 swv[2][2];
; #pragma unroll
;         for (int bj = 0; bj < 2; ++bj)
; #pragma unroll
;             for (int n = 0; n < 2; ++n) swv[bj][n] = *(const f32x4*)(sw + col0 + bj * 128 + n * 16);
; #pragma unroll
;         for (int ai = 0; ai < 2; ++ai)
; #pragma unroll
;             for (int m = 0; m < 4; ++m) { const float sav = sa[row0 + ai * 128 + m * 16];
; #pragma unroll
;                 for (int bj = 0; bj < 2; ++bj)
; #pragma unroll
;                     for (int n = 0; n < 2; ++n) { const i32x4 q = __builtin_bit_cast(i32x4, acc[ai][bj][m][n]);
;                         const f32x4 v = (f32x4){(float)q[0], (float)q[1], (float)q[2], (float)q[3]} * swv[bj][n] * sav;
;                         u32x2 o; o.x = cvt_pk_bf16(v[0], v[1]); o.y = cvt_pk_bf16(v[2], v[3]);
;                         *(u32x2*)(base + (size_t)(ai * 128 + m * 16) * 256 + bj * 128 + n * 16) = o; } }
;     }
.LBB0_2887:
	v_lshl_add_u32 v160, s24, 8, v146
	v_and_b32_e32 v161, 1, v235
	v_mul_u32_u24_e32 v161, 12, v161
	v_lshl_add_u32 v161, v235, 2, v161
	v_add_u32_e32 v161, s22, v161
	v_lshlrev_b32_e32 v164, 9, v146
	v_lshl_add_u32 v164, v161, 1, v164
	v_lshl_or_b32 v161, s25, 8, v161
	v_lshlrev_b32_e32 v162, 2, v160
	v_lshlrev_b32_e32 v163, 2, v161
	global_load_dword v168, v162, s[8:9] offset:0
	global_load_dword v169, v162, s[8:9] offset:64
	global_load_dword v170, v162, s[8:9] offset:128
	global_load_dword v171, v162, s[8:9] offset:192
	global_load_dword v172, v162, s[8:9] offset:512
	global_load_dword v173, v162, s[8:9] offset:576
	global_load_dword v174, v162, s[8:9] offset:640
	global_load_dword v175, v162, s[8:9] offset:704
	global_load_dwordx4 v[176:179], v163, s[10:11] offset:0
	global_load_dwordx4 v[180:183], v163, s[10:11] offset:16
	global_load_dwordx4 v[184:187], v163, s[10:11] offset:512
	global_load_dwordx4 v[188:191], v163, s[10:11] offset:528
	s_lshl_b32 s4, s21, 3
	s_add_i32 s4, s4, s20
	s_ashr_i32 s5, s4, 31
	s_lshl_b64 s[4:5], s[4:5], 17
	s_add_u32 s4, s86, s4
	s_addc_u32 s5, s87, s5
	s_add_u32 s4, s4, 0x2a50f000
	s_addc_u32 s5, s5, 0
	v_permlane16_swap_b32_e32 v142, v138
	v_permlane16_swap_b32_e32 v143, v139
	v_permlane16_swap_b32_e32 v144, v140
	v_permlane16_swap_b32_e32 v145, v141
	v_cvt_f32_i32_e32 v142, v142
	v_cvt_f32_i32_e32 v143, v143
	v_cvt_f32_i32_e32 v144, v144
	v_cvt_f32_i32_e32 v145, v145
	v_cvt_f32_i32_e32 v138, v138
	v_cvt_f32_i32_e32 v139, v139
	v_cvt_f32_i32_e32 v140, v140
	v_cvt_f32_i32_e32 v141, v141
	s_waitcnt vmcnt(0)
	v_pk_mul_f32 v[142:143], v[142:143], v[176:177]
	v_pk_mul_f32 v[144:145], v[144:145], v[178:179]
	v_pk_mul_f32 v[138:139], v[138:139], v[180:181]
	v_pk_mul_f32 v[140:141], v[140:141], v[182:183]
	v_mul_f32_e32 v142, v142, v168
	v_mul_f32_e32 v143, v143, v168
	v_mul_f32_e32 v144, v144, v168
	v_mul_f32_e32 v145, v145, v168
	v_mul_f32_e32 v138, v138, v168
	v_mul_f32_e32 v139, v139, v168
	v_mul_f32_e32 v140, v140, v168
	v_mul_f32_e32 v141, v141, v168
	v_cvt_pk_bf16_f32 v142, v142, v143
	v_cvt_pk_bf16_f32 v143, v144, v145
	v_cvt_pk_bf16_f32 v144, v138, v139
	v_cvt_pk_bf16_f32 v145, v140, v141
	v_mov_b32_e32 v165, v164
	global_store_dwordx4 v165, v[142:145], s[4:5] offset:0
	v_permlane16_swap_b32_e32 v134, v130
	v_permlane16_swap_b32_e32 v135, v131
	v_permlane16_swap_b32_e32 v136, v132
	v_permlane16_swap_b32_e32 v137, v133
	v_cvt_f32_i32_e32 v134, v134
	v_cvt_f32_i32_e32 v135, v135
	v_cvt_f32_i32_e32 v136, v136
	v_cvt_f32_i32_e32 v137, v137
	v_cvt_f32_i32_e32 v130, v130
	v_cvt_f32_i32_e32 v131, v131
	v_cvt_f32_i32_e32 v132, v132
	v_cvt_f32_i32_e32 v133, v133
	v_pk_mul_f32 v[134:135], v[134:135], v[184:185]
	v_pk_mul_f32 v[136:137], v[136:137], v[186:187]
	v_pk_mul_f32 v[130:131], v[130:131], v[188:189]
	v_pk_mul_f32 v[132:133], v[132:133], v[190:191]
	v_mul_f32_e32 v134, v134, v168
	v_mul_f32_e32 v135, v135, v168
	v_mul_f32_e32 v136, v136, v168
	v_mul_f32_e32 v137, v137, v168
	v_mul_f32_e32 v130, v130, v168
	v_mul_f32_e32 v131, v131, v168
	v_mul_f32_e32 v132, v132, v168
	v_mul_f32_e32 v133, v133, v168
	v_cvt_pk_bf16_f32 v134, v134, v135
	v_cvt_pk_bf16_f32 v135, v136, v137
	v_cvt_pk_bf16_f32 v136, v130, v131
	v_cvt_pk_bf16_f32 v137, v132, v133
	v_mov_b32_e32 v166, v164
	global_store_dwordx4 v166, v[134:137], s[4:5] offset:256
	v_permlane16_swap_b32_e32 v126, v122
	v_permlane16_swap_b32_e32 v127, v123
	v_permlane16_swap_b32_e32 v128, v124
	v_permlane16_swap_b32_e32 v129, v125
	v_cvt_f32_i32_e32 v126, v126
	v_cvt_f32_i32_e32 v127, v127
	v_cvt_f32_i32_e32 v128, v128
	v_cvt_f32_i32_e32 v129, v129
	v_cvt_f32_i32_e32 v122, v122
	v_cvt_f32_i32_e32 v123, v123
	v_cvt_f32_i32_e32 v124, v124
	v_cvt_f32_i32_e32 v125, v125
	v_pk_mul_f32 v[126:127], v[126:127], v[176:177]
	v_pk_mul_f32 v[128:129], v[128:129], v[178:179]
	v_pk_mul_f32 v[122:123], v[122:123], v[180:181]
	v_pk_mul_f32 v[124:125], v[124:125], v[182:183]
	v_mul_f32_e32 v126, v126, v169
	v_mul_f32_e32 v127, v127, v169
	v_mul_f32_e32 v128, v128, v169
	v_mul_f32_e32 v129, v129, v169
	v_mul_f32_e32 v122, v122, v169
	v_mul_f32_e32 v123, v123, v169
	v_mul_f32_e32 v124, v124, v169
	v_mul_f32_e32 v125, v125, v169
	v_cvt_pk_bf16_f32 v126, v126, v127
	v_cvt_pk_bf16_f32 v127, v128, v129
	v_cvt_pk_bf16_f32 v128, v122, v123
	v_cvt_pk_bf16_f32 v129, v124, v125
	v_add_u32_e32 v165, 0x2000, v164
	global_store_dwordx4 v165, v[126:129], s[4:5] offset:0
	v_permlane16_swap_b32_e32 v102, v98
	v_permlane16_swap_b32_e32 v103, v99
	v_permlane16_swap_b32_e32 v104, v100
	v_permlane16_swap_b32_e32 v105, v101
	v_cvt_f32_i32_e32 v102, v102
	v_cvt_f32_i32_e32 v103, v103
	v_cvt_f32_i32_e32 v104, v104
	v_cvt_f32_i32_e32 v105, v105
	v_cvt_f32_i32_e32 v98, v98
	v_cvt_f32_i32_e32 v99, v99
	v_cvt_f32_i32_e32 v100, v100
	v_cvt_f32_i32_e32 v101, v101
	v_pk_mul_f32 v[102:103], v[102:103], v[184:185]
	v_pk_mul_f32 v[104:105], v[104:105], v[186:187]
	v_pk_mul_f32 v[98:99], v[98:99], v[188:189]
	v_pk_mul_f32 v[100:101], v[100:101], v[190:191]
	v_mul_f32_e32 v102, v102, v169
	v_mul_f32_e32 v103, v103, v169
	v_mul_f32_e32 v104, v104, v169
	v_mul_f32_e32 v105, v105, v169
	v_mul_f32_e32 v98, v98, v169
	v_mul_f32_e32 v99, v99, v169
	v_mul_f32_e32 v100, v100, v169
	v_mul_f32_e32 v101, v101, v169
	v_cvt_pk_bf16_f32 v102, v102, v103
	v_cvt_pk_bf16_f32 v103, v104, v105
	v_cvt_pk_bf16_f32 v104, v98, v99
	v_cvt_pk_bf16_f32 v105, v100, v101
	v_add_u32_e32 v166, 0x2000, v164
	global_store_dwordx4 v166, v[102:105], s[4:5] offset:256
	v_permlane16_swap_b32_e32 v94, v90
	v_permlane16_swap_b32_e32 v95, v91
	v_permlane16_swap_b32_e32 v96, v92
	v_permlane16_swap_b32_e32 v97, v93
	v_cvt_f32_i32_e32 v94, v94
; __device__ __forceinline__ unsigned cvt_pk_bf16(float lo, float hi) { unsigned r; asm("v_cvt_pk_bf16_f32 %0, %1, %2" : "=v"(r) : "v"(lo), "v"(hi)); return r; }
;     __device__ __forceinline__ void operator()(const f32x4 (&acc)[2][2][4][2], const pg8::Unit& u, int wr, int wc, int fr, int fq) const {
;     ...
;             for (int m = 0; m < 4; ++m) { const float sav = sa[row0 + ai * 128 + m * 16];
; #pragma unroll
;                 for (int bj = 0; bj < 2; ++bj)
; #pragma unroll
;                     for (int n = 0; n < 2; ++n) { const i32x4 q = __builtin_bit_cast(i32x4, acc[ai][bj][m][n]);
;                         const f32x4 v = (f32x4){(float)q[0], (float)q[1], (float)q[2], (float)q[3]} * swv[bj][n] * sav;
;                         u32x2 o; o.x = cvt_pk_bf16(v[0], v[1]); o.y = cvt_pk_bf16(v[2], v[3]);
;                         *(u32x2*)(base + (size_t)(ai * 128 + m * 16) * 256 + bj * 128 + n * 16) = o; } }
;     }
	v_cvt_f32_i32_e32 v95, v95
	v_cvt_f32_i32_e32 v96, v96
	v_cvt_f32_i32_e32 v97, v97
	v_cvt_f32_i32_e32 v90, v90
	v_cvt_f32_i32_e32 v91, v91
	v_cvt_f32_i32_e32 v92, v92
	v_cvt_f32_i32_e32 v93, v93
	v_pk_mul_f32 v[94:95], v[94:95], v[176:177]
	v_pk_mul_f32 v[96:97], v[96:97], v[178:179]
	v_pk_mul_f32 v[90:91], v[90:91], v[180:181]
	v_pk_mul_f32 v[92:93], v[92:93], v[182:183]
	v_mul_f32_e32 v94, v94, v170
	v_mul_f32_e32 v95, v95, v170
	v_mul_f32_e32 v96, v96, v170
	v_mul_f32_e32 v97, v97, v170
	v_mul_f32_e32 v90, v90, v170
	v_mul_f32_e32 v91, v91, v170
	v_mul_f32_e32 v92, v92, v170
	v_mul_f32_e32 v93, v93, v170
	v_cvt_pk_bf16_f32 v94, v94, v95
	v_cvt_pk_bf16_f32 v95, v96, v97
	v_cvt_pk_bf16_f32 v96, v90, v91
	v_cvt_pk_bf16_f32 v97, v92, v93
	v_add_u32_e32 v165, 0x4000, v164
	global_store_dwordx4 v165, v[94:97], s[4:5] offset:0
	v_permlane16_swap_b32_e32 v86, v82
	v_permlane16_swap_b32_e32 v87, v83
	v_permlane16_swap_b32_e32 v88, v84
	v_permlane16_swap_b32_e32 v89, v85
	v_cvt_f32_i32_e32 v86, v86
	v_cvt_f32_i32_e32 v87, v87
	v_cvt_f32_i32_e32 v88, v88
	v_cvt_f32_i32_e32 v89, v89
	v_cvt_f32_i32_e32 v82, v82
	v_cvt_f32_i32_e32 v83, v83
	v_cvt_f32_i32_e32 v84, v84
	v_cvt_f32_i32_e32 v85, v85
	v_pk_mul_f32 v[86:87], v[86:87], v[184:185]
	v_pk_mul_f32 v[88:89], v[88:89], v[186:187]
	v_pk_mul_f32 v[82:83], v[82:83], v[188:189]
	v_pk_mul_f32 v[84:85], v[84:85], v[190:191]
	v_mul_f32_e32 v86, v86, v170
	v_mul_f32_e32 v87, v87, v170
	v_mul_f32_e32 v88, v88, v170
	v_mul_f32_e32 v89, v89, v170
	v_mul_f32_e32 v82, v82, v170
	v_mul_f32_e32 v83, v83, v170
	v_mul_f32_e32 v84, v84, v170
	v_mul_f32_e32 v85, v85, v170
	v_cvt_pk_bf16_f32 v86, v86, v87
	v_cvt_pk_bf16_f32 v87, v88, v89
	v_cvt_pk_bf16_f32 v88, v82, v83
	v_cvt_pk_bf16_f32 v89, v84, v85
	v_add_u32_e32 v166, 0x4000, v164
	global_store_dwordx4 v166, v[86:89], s[4:5] offset:256
	v_permlane16_swap_b32_e32 v78, v74
	v_permlane16_swap_b32_e32 v79, v75
	v_permlane16_swap_b32_e32 v80, v76
	v_permlane16_swap_b32_e32 v81, v77
	v_cvt_f32_i32_e32 v78, v78
	v_cvt_f32_i32_e32 v79, v79
	v_cvt_f32_i32_e32 v80, v80
	v_cvt_f32_i32_e32 v81, v81
	v_cvt_f32_i32_e32 v74, v74
	v_cvt_f32_i32_e32 v75, v75
	v_cvt_f32_i32_e32 v76, v76
	v_cvt_f32_i32_e32 v77, v77
	v_pk_mul_f32 v[78:79], v[78:79], v[176:177]
	v_pk_mul_f32 v[80:81], v[80:81], v[178:179]
	v_pk_mul_f32 v[74:75], v[74:75], v[180:181]
	v_pk_mul_f32 v[76:77], v[76:77], v[182:183]
	v_mul_f32_e32 v78, v78, v171
	v_mul_f32_e32 v79, v79, v171
	v_mul_f32_e32 v80, v80, v171
	v_mul_f32_e32 v81, v81, v171
	v_mul_f32_e32 v74, v74, v171
	v_mul_f32_e32 v75, v75, v171
	v_mul_f32_e32 v76, v76, v171
	v_mul_f32_e32 v77, v77, v171
	v_cvt_pk_bf16_f32 v78, v78, v79
	v_cvt_pk_bf16_f32 v79, v80, v81
	v_cvt_pk_bf16_f32 v80, v74, v75
	v_cvt_pk_bf16_f32 v81, v76, v77
	v_add_u32_e32 v165, 0x6000, v164
	global_store_dwordx4 v165, v[78:81], s[4:5] offset:0
	v_permlane16_swap_b32_e32 v70, v66
	v_permlane16_swap_b32_e32 v71, v67
	v_permlane16_swap_b32_e32 v72, v68
	v_permlane16_swap_b32_e32 v73, v69
	v_cvt_f32_i32_e32 v70, v70
	v_cvt_f32_i32_e32 v71, v71
	v_cvt_f32_i32_e32 v72, v72
	v_cvt_f32_i32_e32 v73, v73
	v_cvt_f32_i32_e32 v66, v66
	v_cvt_f32_i32_e32 v67, v67
	v_cvt_f32_i32_e32 v68, v68
	v_cvt_f32_i32_e32 v69, v69
	v_pk_mul_f32 v[70:71], v[70:71], v[184:185]
	v_pk_mul_f32 v[72:73], v[72:73], v[186:187]
	v_pk_mul_f32 v[66:67], v[66:67], v[188:189]
	v_pk_mul_f32 v[68:69], v[68:69], v[190:191]
	v_mul_f32_e32 v70, v70, v171
	v_mul_f32_e32 v71, v71, v171
	v_mul_f32_e32 v72, v72, v171
	v_mul_f32_e32 v73, v73, v171
	v_mul_f32_e32 v66, v66, v171
	v_mul_f32_e32 v67, v67, v171
	v_mul_f32_e32 v68, v68, v171
	v_mul_f32_e32 v69, v69, v171
	v_cvt_pk_bf16_f32 v70, v70, v71
	v_cvt_pk_bf16_f32 v71, v72, v73
	v_cvt_pk_bf16_f32 v72, v66, v67
	v_cvt_pk_bf16_f32 v73, v68, v69
	v_add_u32_e32 v166, 0x6000, v164
	global_store_dwordx4 v166, v[70:73], s[4:5] offset:256
	v_permlane16_swap_b32_e32 v62, v58
	v_permlane16_swap_b32_e32 v63, v59
	v_permlane16_swap_b32_e32 v64, v60
	v_permlane16_swap_b32_e32 v65, v61
	v_cvt_f32_i32_e32 v62, v62
	v_cvt_f32_i32_e32 v63, v63
	v_cvt_f32_i32_e32 v64, v64
	v_cvt_f32_i32_e32 v65, v65
	v_cvt_f32_i32_e32 v58, v58
	v_cvt_f32_i32_e32 v59, v59
	v_cvt_f32_i32_e32 v60, v60
	v_cvt_f32_i32_e32 v61, v61
	v_pk_mul_f32 v[62:63], v[62:63], v[176:177]
	v_pk_mul_f32 v[64:65], v[64:65], v[178:179]
	v_pk_mul_f32 v[58:59], v[58:59], v[180:181]
	v_pk_mul_f32 v[60:61], v[60:61], v[182:183]
	v_mul_f32_e32 v62, v62, v172
	v_mul_f32_e32 v63, v63, v172
	v_mul_f32_e32 v64, v64, v172
	v_mul_f32_e32 v65, v65, v172
	v_mul_f32_e32 v58, v58, v172
	v_mul_f32_e32 v59, v59, v172
	v_mul_f32_e32 v60, v60, v172
	v_mul_f32_e32 v61, v61, v172
	v_cvt_pk_bf16_f32 v62, v62, v63
	v_cvt_pk_bf16_f32 v63, v64, v65
	v_cvt_pk_bf16_f32 v64, v58, v59
	v_cvt_pk_bf16_f32 v65, v60, v61
	v_add_u32_e32 v165, 0x10000, v164
	global_store_dwordx4 v165, v[62:65], s[4:5] offset:0
	v_permlane16_swap_b32_e32 v54, v50
	v_permlane16_swap_b32_e32 v55, v51
	v_permlane16_swap_b32_e32 v56, v52
	v_permlane16_swap_b32_e32 v57, v53
	v_cvt_f32_i32_e32 v54, v54
	v_cvt_f32_i32_e32 v55, v55
	v_cvt_f32_i32_e32 v56, v56
	v_cvt_f32_i32_e32 v57, v57
	v_cvt_f32_i32_e32 v50, v50
	v_cvt_f32_i32_e32 v51, v51
	v_cvt_f32_i32_e32 v52, v52
	v_cvt_f32_i32_e32 v53, v53
	v_pk_mul_f32 v[54:55], v[54:55], v[184:185]
	v_pk_mul_f32 v[56:57], v[56:57], v[186:187]
	v_pk_mul_f32 v[50:51], v[50:51], v[188:189]
	v_pk_mul_f32 v[52:53], v[52:53], v[190:191]
	v_mul_f32_e32 v54, v54, v172
	v_mul_f32_e32 v55, v55, v172
	v_mul_f32_e32 v56, v56, v172
	v_mul_f32_e32 v57, v57, v172
	v_mul_f32_e32 v50, v50, v172
	v_mul_f32_e32 v51, v51, v172
	v_mul_f32_e32 v52, v52, v172
; __device__ __forceinline__ unsigned cvt_pk_bf16(float lo, float hi) { unsigned r; asm("v_cvt_pk_bf16_f32 %0, %1, %2" : "=v"(r) : "v"(lo), "v"(hi)); return r; }
;     __device__ __forceinline__ void operator()(const f32x4 (&acc)[2][2][4][2], const pg8::Unit& u, int wr, int wc, int fr, int fq) const {
;     ...
;             for (int m = 0; m < 4; ++m) { const float sav = sa[row0 + ai * 128 + m * 16];
; #pragma unroll
;                 for (int bj = 0; bj < 2; ++bj)
; #pragma unroll
;                     for (int n = 0; n < 2; ++n) { const i32x4 q = __builtin_bit_cast(i32x4, acc[ai][bj][m][n]);
;                         const f32x4 v = (f32x4){(float)q[0], (float)q[1], (float)q[2], (float)q[3]} * swv[bj][n] * sav;
;                         u32x2 o; o.x = cvt_pk_bf16(v[0], v[1]); o.y = cvt_pk_bf16(v[2], v[3]);
;                         *(u32x2*)(base + (size_t)(ai * 128 + m * 16) * 256 + bj * 128 + n * 16) = o; } }
;     }
	v_mul_f32_e32 v53, v53, v172
	v_cvt_pk_bf16_f32 v54, v54, v55
	v_cvt_pk_bf16_f32 v55, v56, v57
	v_cvt_pk_bf16_f32 v56, v50, v51
	v_cvt_pk_bf16_f32 v57, v52, v53
	v_add_u32_e32 v166, 0x10000, v164
	global_store_dwordx4 v166, v[54:57], s[4:5] offset:256
	v_permlane16_swap_b32_e32 v46, v42
	v_permlane16_swap_b32_e32 v47, v43
	v_permlane16_swap_b32_e32 v48, v44
	v_permlane16_swap_b32_e32 v49, v45
	v_cvt_f32_i32_e32 v46, v46
	v_cvt_f32_i32_e32 v47, v47
	v_cvt_f32_i32_e32 v48, v48
	v_cvt_f32_i32_e32 v49, v49
	v_cvt_f32_i32_e32 v42, v42
	v_cvt_f32_i32_e32 v43, v43
	v_cvt_f32_i32_e32 v44, v44
	v_cvt_f32_i32_e32 v45, v45
	v_pk_mul_f32 v[46:47], v[46:47], v[176:177]
	v_pk_mul_f32 v[48:49], v[48:49], v[178:179]
	v_pk_mul_f32 v[42:43], v[42:43], v[180:181]
	v_pk_mul_f32 v[44:45], v[44:45], v[182:183]
	v_mul_f32_e32 v46, v46, v173
	v_mul_f32_e32 v47, v47, v173
	v_mul_f32_e32 v48, v48, v173
	v_mul_f32_e32 v49, v49, v173
	v_mul_f32_e32 v42, v42, v173
	v_mul_f32_e32 v43, v43, v173
	v_mul_f32_e32 v44, v44, v173
	v_mul_f32_e32 v45, v45, v173
	v_cvt_pk_bf16_f32 v46, v46, v47
	v_cvt_pk_bf16_f32 v47, v48, v49
	v_cvt_pk_bf16_f32 v48, v42, v43
	v_cvt_pk_bf16_f32 v49, v44, v45
	v_add_u32_e32 v165, 0x12000, v164
	global_store_dwordx4 v165, v[46:49], s[4:5] offset:0
	v_permlane16_swap_b32_e32 v38, v34
	v_permlane16_swap_b32_e32 v39, v35
	v_permlane16_swap_b32_e32 v40, v36
	v_permlane16_swap_b32_e32 v41, v37
	v_cvt_f32_i32_e32 v38, v38
	v_cvt_f32_i32_e32 v39, v39
	v_cvt_f32_i32_e32 v40, v40
	v_cvt_f32_i32_e32 v41, v41
	v_cvt_f32_i32_e32 v34, v34
	v_cvt_f32_i32_e32 v35, v35
	v_cvt_f32_i32_e32 v36, v36
	v_cvt_f32_i32_e32 v37, v37
	v_pk_mul_f32 v[38:39], v[38:39], v[184:185]
	v_pk_mul_f32 v[40:41], v[40:41], v[186:187]
	v_pk_mul_f32 v[34:35], v[34:35], v[188:189]
	v_pk_mul_f32 v[36:37], v[36:37], v[190:191]
	v_mul_f32_e32 v38, v38, v173
	v_mul_f32_e32 v39, v39, v173
	v_mul_f32_e32 v40, v40, v173
	v_mul_f32_e32 v41, v41, v173
	v_mul_f32_e32 v34, v34, v173
	v_mul_f32_e32 v35, v35, v173
	v_mul_f32_e32 v36, v36, v173
	v_mul_f32_e32 v37, v37, v173
	v_cvt_pk_bf16_f32 v38, v38, v39
	v_cvt_pk_bf16_f32 v39, v40, v41
	v_cvt_pk_bf16_f32 v40, v34, v35
	v_cvt_pk_bf16_f32 v41, v36, v37
	v_add_u32_e32 v166, 0x12000, v164
	global_store_dwordx4 v166, v[38:41], s[4:5] offset:256
	v_permlane16_swap_b32_e32 v30, v26
	v_permlane16_swap_b32_e32 v31, v27
	v_permlane16_swap_b32_e32 v32, v28
	v_permlane16_swap_b32_e32 v33, v29
	v_cvt_f32_i32_e32 v30, v30
	v_cvt_f32_i32_e32 v31, v31
	v_cvt_f32_i32_e32 v32, v32
	v_cvt_f32_i32_e32 v33, v33
	v_cvt_f32_i32_e32 v26, v26
	v_cvt_f32_i32_e32 v27, v27
	v_cvt_f32_i32_e32 v28, v28
	v_cvt_f32_i32_e32 v29, v29
	v_pk_mul_f32 v[30:31], v[30:31], v[176:177]
	v_pk_mul_f32 v[32:33], v[32:33], v[178:179]
	v_pk_mul_f32 v[26:27], v[26:27], v[180:181]
	v_pk_mul_f32 v[28:29], v[28:29], v[182:183]
	v_mul_f32_e32 v30, v30, v174
	v_mul_f32_e32 v31, v31, v174
	v_mul_f32_e32 v32, v32, v174
	v_mul_f32_e32 v33, v33, v174
	v_mul_f32_e32 v26, v26, v174
	v_mul_f32_e32 v27, v27, v174
	v_mul_f32_e32 v28, v28, v174
	v_mul_f32_e32 v29, v29, v174
	v_cvt_pk_bf16_f32 v30, v30, v31
	v_cvt_pk_bf16_f32 v31, v32, v33
	v_cvt_pk_bf16_f32 v32, v26, v27
	v_cvt_pk_bf16_f32 v33, v28, v29
	v_add_u32_e32 v165, 0x14000, v164
	global_store_dwordx4 v165, v[30:33], s[4:5] offset:0
	v_permlane16_swap_b32_e32 v22, v18
	v_permlane16_swap_b32_e32 v23, v19
	v_permlane16_swap_b32_e32 v24, v20
	v_permlane16_swap_b32_e32 v25, v21
	v_cvt_f32_i32_e32 v22, v22
	v_cvt_f32_i32_e32 v23, v23
	v_cvt_f32_i32_e32 v24, v24
	v_cvt_f32_i32_e32 v25, v25
	v_cvt_f32_i32_e32 v18, v18
	v_cvt_f32_i32_e32 v19, v19
	v_cvt_f32_i32_e32 v20, v20
	v_cvt_f32_i32_e32 v21, v21
	v_pk_mul_f32 v[22:23], v[22:23], v[184:185]
	v_pk_mul_f32 v[24:25], v[24:25], v[186:187]
	v_pk_mul_f32 v[18:19], v[18:19], v[188:189]
	v_pk_mul_f32 v[20:21], v[20:21], v[190:191]
	v_mul_f32_e32 v22, v22, v174
	v_mul_f32_e32 v23, v23, v174
	v_mul_f32_e32 v24, v24, v174
	v_mul_f32_e32 v25, v25, v174
	v_mul_f32_e32 v18, v18, v174
	v_mul_f32_e32 v19, v19, v174
	v_mul_f32_e32 v20, v20, v174
	v_mul_f32_e32 v21, v21, v174
	v_cvt_pk_bf16_f32 v22, v22, v23
	v_cvt_pk_bf16_f32 v23, v24, v25
	v_cvt_pk_bf16_f32 v24, v18, v19
	v_cvt_pk_bf16_f32 v25, v20, v21
	v_add_u32_e32 v166, 0x14000, v164
	global_store_dwordx4 v166, v[22:25], s[4:5] offset:256
	v_permlane16_swap_b32_e32 v14, v10
	v_permlane16_swap_b32_e32 v15, v11
	v_permlane16_swap_b32_e32 v16, v12
	v_permlane16_swap_b32_e32 v17, v13
	v_cvt_f32_i32_e32 v14, v14
	v_cvt_f32_i32_e32 v15, v15
	v_cvt_f32_i32_e32 v16, v16
	v_cvt_f32_i32_e32 v17, v17
	v_cvt_f32_i32_e32 v10, v10
	v_cvt_f32_i32_e32 v11, v11
	v_cvt_f32_i32_e32 v12, v12
	v_cvt_f32_i32_e32 v13, v13
	v_pk_mul_f32 v[14:15], v[14:15], v[176:177]
	v_pk_mul_f32 v[16:17], v[16:17], v[178:179]
	v_pk_mul_f32 v[10:11], v[10:11], v[180:181]
	v_pk_mul_f32 v[12:13], v[12:13], v[182:183]
	v_mul_f32_e32 v14, v14, v175
	v_mul_f32_e32 v15, v15, v175
	v_mul_f32_e32 v16, v16, v175
	v_mul_f32_e32 v17, v17, v175
	v_mul_f32_e32 v10, v10, v175
	v_mul_f32_e32 v11, v11, v175
	v_mul_f32_e32 v12, v12, v175
	v_mul_f32_e32 v13, v13, v175
	v_cvt_pk_bf16_f32 v14, v14, v15
	v_cvt_pk_bf16_f32 v15, v16, v17
	v_cvt_pk_bf16_f32 v16, v10, v11
	v_cvt_pk_bf16_f32 v17, v12, v13
	v_add_u32_e32 v165, 0x16000, v164
	global_store_dwordx4 v165, v[14:17], s[4:5] offset:0
	v_permlane16_swap_b32_e32 v6, v2
	v_permlane16_swap_b32_e32 v7, v3
	v_permlane16_swap_b32_e32 v8, v4
	v_permlane16_swap_b32_e32 v9, v5
	v_cvt_f32_i32_e32 v6, v6
	v_cvt_f32_i32_e32 v7, v7
	v_cvt_f32_i32_e32 v8, v8
	v_cvt_f32_i32_e32 v9, v9
	v_cvt_f32_i32_e32 v2, v2
	v_cvt_f32_i32_e32 v3, v3
	v_cvt_f32_i32_e32 v4, v4
	v_cvt_f32_i32_e32 v5, v5
	v_pk_mul_f32 v[6:7], v[6:7], v[184:185]
	v_pk_mul_f32 v[8:9], v[8:9], v[186:187]
	v_pk_mul_f32 v[2:3], v[2:3], v[188:189]
	v_pk_mul_f32 v[4:5], v[4:5], v[190:191]
	v_mul_f32_e32 v6, v6, v175
	v_mul_f32_e32 v7, v7, v175
	v_mul_f32_e32 v8, v8, v175
	v_mul_f32_e32 v9, v9, v175
	v_mul_f32_e32 v2, v2, v175
	v_mul_f32_e32 v3, v3, v175
	v_mul_f32_e32 v4, v4, v175
	v_mul_f32_e32 v5, v5, v175
	v_cvt_pk_bf16_f32 v6, v6, v7
	v_cvt_pk_bf16_f32 v7, v8, v9
	v_cvt_pk_bf16_f32 v8, v2, v3
	v_cvt_pk_bf16_f32 v9, v4, v5
	v_add_u32_e32 v166, 0x16000, v164
	global_store_dwordx4 v166, v[6:9], s[4:5] offset:256
	s_waitcnt vmcnt(0)
	s_barrier
